# c8 + RG-LRU local pass: scan results kept in registers across the barrier, batched segment-scan and carry-in LDS reads, global instead of flat stores/loads
# speedup vs baseline: 1.0093x; 1.0093x over previous
; DEVI float bflo(unsigned w) { return __uint_as_float(w << 16); }
; DEVI float bfhi(unsigned w) { return __uint_as_float(w & 0xffff0000u); }
; #define RNN_LOAD(j_) do { const int b_ = (j_) >> 7, t0_ = ((j_) & 127) * 128; _Pragma("unroll") for (int k = 0; k < 4; ++k) { const int s_ = t0_ + tok - 3 + k; \
;         const bf16_t* p_ = xr + ((size_t)b_ * SEQ + (s_ < 0 ? 0 : s_)) * DM + ch0 + cg4; xw[2 * k] = *(const u32x4*)p_; xw[2 * k + 1] = *(const u32x4*)(p_ + 8); } } while (0)
; DEVI void rnn_local_phase(const bf16_t* xr, const float* convw, const float* convb, const bf16_t* lruT, const float* ba, const float* bx, const float* lam,
;                           bf16_t* hloc, bf16_t* pcum, float* aggA, float* aggH, char* lds, int wv) {
;     ...
;     int j = slot;
;     if (j < 256) RNN_LOAD(j);
;     __syncthreads();
;     for (; j < 256; j += ns) {
;         const int b = j >> 7, chunk = j & 127, t0 = chunk * 128;
;         {
;             float xc[16];
; #pragma unroll
;             for (int i = 0; i < 16; i += 4) { const f32x4 bb = *(const f32x4*)(cwL + 256 + cg4 + i); xc[i] = bb[0]; xc[i + 1] = bb[1]; xc[i + 2] = bb[2]; xc[i + 3] = bb[3]; }
; #pragma unroll
;             for (int k = 0; k < 4; ++k) { const float zf = (t0 + tok - 3 + k) >= 0 ? 1.f : 0.f; const u32x4 w0 = xw[2 * k], w1 = xw[2 * k + 1];
;                 const float xv[16] = {bflo(w0.x), bfhi(w0.x), bflo(w0.y), bfhi(w0.y), bflo(w0.z), bfhi(w0.z), bflo(w0.w), bfhi(w0.w), bflo(w1.x), bfhi(w1.x), bflo(w1.y), bfhi(w1.y), bflo(w1.z), bfhi(w1.z), bflo(w1.w), bfhi(w1.w)};
; #pragma unroll
;                 for (int i = 0; i < 16; i += 4) { const f32x4 cw = *(const f32x4*)(cwL + k * 64 + cg4 + i) * zf; xc[i] += cw[0] * xv[i]; xc[i + 1] += cw[1] * xv[i + 1]; xc[i + 2] += cw[2] * xv[i + 2]; xc[i + 3] += cw[3] * xv[i + 3]; } }
;             if (j + ns < 256) RNN_LOAD(j + ns);
.LBB0_121:
	ds_read_b128 v[90:93], v162
	ds_read_b128 v[82:85], v162 offset:16
	ds_read_b128 v[74:77], v162 offset:32
	ds_read_b128 v[66:69], v162 offset:48
	ds_read_b128 v[142:145], v163
	ds_read_b128 v[138:141], v163 offset:16
	ds_read_b128 v[134:137], v163 offset:32
	ds_read_b128 v[130:133], v163 offset:48
	ds_read_b128 v[126:129], v163 offset:256
	ds_read_b128 v[122:125], v163 offset:272
	ds_read_b128 v[118:121], v163 offset:288
	ds_read_b128 v[114:117], v163 offset:304
	ds_read_b128 v[110:113], v163 offset:512
	ds_read_b128 v[106:109], v163 offset:528
	ds_read_b128 v[102:105], v163 offset:544
	ds_read_b128 v[98:101], v163 offset:560
	ds_read_b128 v[94:97], v163 offset:768
	ds_read_b128 v[86:89], v163 offset:784
	ds_read_b128 v[78:81], v163 offset:800
	ds_read_b128 v[70:73], v163 offset:816
	s_add_i32 s77, s60, s24
	s_cmpk_gt_i32 s77, 0xff
	s_cselect_b64 s[8:9], -1, 0
	s_and_b64 vcc, exec, s[8:9]
	s_cbranch_vccnz .LBB0_123
	s_lshl_b32 s11, s77, 7
	s_and_b32 s78, s11, 0x3f80
	v_add_u32_e32 v18, s78, v164
	v_max_i32_e32 v0, 0, v18
	v_lshlrev_b64 v[2:3], 11, v[0:1]
	v_max_i32_e32 v0, -1, v18
	v_add_u32_e32 v0, 1, v0
	v_lshlrev_b64 v[10:11], 11, v[0:1]
	v_max_i32_e32 v0, -2, v18
	s_ashr_i32 s10, s77, 7
	v_add_u32_e32 v0, 2, v0
	s_ashr_i32 s11, s10, 31
	v_lshlrev_b64 v[18:19], 11, v[0:1]
	v_add_u32_e32 v0, s78, v157
	s_lshl_b64 s[10:11], s[10:11], 25
	v_max_i32_e32 v0, 0, v0
	v_lshl_add_u64 v[26:27], v[146:147], 0, s[10:11]
	v_lshlrev_b64 v[28:29], 11, v[0:1]
	v_lshl_add_u64 v[2:3], v[26:27], 0, v[2:3]
	v_lshl_add_u64 v[10:11], v[26:27], 0, v[10:11]
	v_lshl_add_u64 v[18:19], v[26:27], 0, v[18:19]
	v_lshl_add_u64 v[26:27], v[26:27], 0, v[28:29]
	global_load_dwordx4 v[6:9], v[2:3], off
	s_nop 0
	global_load_dwordx4 v[2:5], v[2:3], off offset:16
	s_nop 0
	global_load_dwordx4 v[14:17], v[10:11], off
	s_nop 0
	global_load_dwordx4 v[10:13], v[10:11], off offset:16
	s_nop 0
	global_load_dwordx4 v[22:25], v[18:19], off
	s_nop 0
	global_load_dwordx4 v[18:21], v[18:19], off offset:16
	s_nop 0
	global_load_dwordx4 v[30:33], v[26:27], off
	s_nop 0
	global_load_dwordx4 v[26:29], v[26:27], off offset:16
.LBB0_123:
	s_and_b32 s78, s60, 0x7f
	s_lshl_b32 s79, s78, 7
	v_add_u32_e32 v196, s79, v157
	v_cmp_lt_i32_e32 vcc, 2, v196
	v_and_b32_e32 v197, 0xffff0000, v62
	s_nop 0
	v_cndmask_b32_e64 v0, 0, 1.0, vcc
	v_cmp_lt_i32_e32 vcc, 1, v196
	s_waitcnt lgkmcnt(0)
	v_pk_mul_f32 v[144:145], v[144:145], v[0:1] op_sel_hi:[1,0]
	v_pk_mul_f32 v[142:143], v[142:143], v[0:1] op_sel_hi:[1,0]
	v_pk_mul_f32 v[140:141], v[140:141], v[0:1] op_sel_hi:[1,0]
	v_pk_mul_f32 v[138:139], v[138:139], v[0:1] op_sel_hi:[1,0]
	v_pk_mul_f32 v[136:137], v[0:1], v[136:137] op_sel_hi:[0,1]
	v_pk_mul_f32 v[134:135], v[0:1], v[134:135] op_sel_hi:[0,1]
	v_pk_mul_f32 v[132:133], v[0:1], v[132:133] op_sel_hi:[0,1]
	v_pk_mul_f32 v[130:131], v[0:1], v[130:131] op_sel_hi:[0,1]
	v_cndmask_b32_e64 v0, 0, 1.0, vcc
	v_cmp_lt_i32_e32 vcc, 0, v196
	v_pk_mul_f32 v[128:129], v[0:1], v[128:129] op_sel_hi:[0,1]
	v_pk_mul_f32 v[126:127], v[0:1], v[126:127] op_sel_hi:[0,1]
	v_pk_mul_f32 v[124:125], v[0:1], v[124:125] op_sel_hi:[0,1]
	v_pk_mul_f32 v[122:123], v[0:1], v[122:123] op_sel_hi:[0,1]
	v_pk_mul_f32 v[120:121], v[0:1], v[120:121] op_sel_hi:[0,1]
	v_pk_mul_f32 v[118:119], v[0:1], v[118:119] op_sel_hi:[0,1]
	v_pk_mul_f32 v[116:117], v[0:1], v[116:117] op_sel_hi:[0,1]
	v_pk_mul_f32 v[114:115], v[0:1], v[114:115] op_sel_hi:[0,1]
	v_cndmask_b32_e64 v0, 0, 1.0, vcc
	v_cmp_lt_i32_e32 vcc, -1, v196
	v_lshlrev_b32_e32 v196, 16, v62
	v_lshlrev_b32_e32 v62, 16, v63
	v_and_b32_e32 v63, 0xffff0000, v63
	v_pk_fma_f32 v[90:91], v[142:143], v[196:197], v[90:91]
	v_lshlrev_b32_e32 v142, 16, v58
	v_and_b32_e32 v143, 0xffff0000, v58
	v_pk_fma_f32 v[62:63], v[144:145], v[62:63], v[92:93]
	v_lshlrev_b32_e32 v58, 16, v59
	v_and_b32_e32 v59, 0xffff0000, v59
	v_pk_fma_f32 v[58:59], v[128:129], v[58:59], v[62:63]
	v_lshlrev_b32_e32 v62, 16, v64
	v_and_b32_e32 v63, 0xffff0000, v64
	v_pk_fma_f32 v[62:63], v[138:139], v[62:63], v[82:83]
	v_lshlrev_b32_e32 v82, 16, v60
	v_and_b32_e32 v83, 0xffff0000, v60
	v_pk_mul_f32 v[112:113], v[0:1], v[112:113] op_sel_hi:[0,1]
	v_pk_mul_f32 v[110:111], v[0:1], v[110:111] op_sel_hi:[0,1]
	v_pk_mul_f32 v[108:109], v[0:1], v[108:109] op_sel_hi:[0,1]
	v_pk_mul_f32 v[106:107], v[0:1], v[106:107] op_sel_hi:[0,1]
	v_pk_mul_f32 v[104:105], v[0:1], v[104:105] op_sel_hi:[0,1]
	v_pk_mul_f32 v[102:103], v[0:1], v[102:103] op_sel_hi:[0,1]
	v_pk_mul_f32 v[100:101], v[0:1], v[100:101] op_sel_hi:[0,1]
	v_pk_mul_f32 v[98:99], v[0:1], v[98:99] op_sel_hi:[0,1]
	v_cndmask_b32_e64 v0, 0, 1.0, vcc
	v_pk_fma_f32 v[90:91], v[126:127], v[142:143], v[90:91]
	v_lshlrev_b32_e32 v126, 16, v54
	v_and_b32_e32 v127, 0xffff0000, v54
	v_lshlrev_b32_e32 v54, 16, v55
	v_and_b32_e32 v55, 0xffff0000, v55
	v_pk_fma_f32 v[62:63], v[122:123], v[82:83], v[62:63]
	v_lshlrev_b32_e32 v82, 16, v56
	v_and_b32_e32 v83, 0xffff0000, v56
	v_pk_fma_f32 v[54:55], v[112:113], v[54:55], v[58:59]
	v_pk_mul_f32 v[58:59], v[0:1], v[86:87] op_sel_hi:[0,1]
	v_pk_fma_f32 v[62:63], v[106:107], v[82:83], v[62:63]
	v_lshlrev_b32_e32 v82, 16, v52
	v_and_b32_e32 v83, 0xffff0000, v52
	v_pk_fma_f32 v[58:59], v[58:59], v[82:83], v[62:63]
	v_lshlrev_b32_e32 v62, 16, v65
	v_and_b32_e32 v63, 0xffff0000, v65
	v_pk_fma_f32 v[62:63], v[140:141], v[62:63], v[84:85]
	v_lshlrev_b32_e32 v60, 16, v61
	v_and_b32_e32 v61, 0xffff0000, v61
	v_pk_fma_f32 v[60:61], v[124:125], v[60:61], v[62:63]
	v_lshlrev_b32_e32 v56, 16, v57
	v_and_b32_e32 v57, 0xffff0000, v57
	v_pk_fma_f32 v[56:57], v[108:109], v[56:57], v[60:61]
	v_lshlrev_b32_e32 v60, 16, v46
	v_and_b32_e32 v61, 0xffff0000, v46
; DEVI float bflo(unsigned w) { return __uint_as_float(w << 16); }
; DEVI void rnn_local_phase(const bf16_t* xr, const float* convw, const float* convb, const bf16_t* lruT, const float* ba, const float* bx, const float* lam,
;                           bf16_t* hloc, bf16_t* pcum, float* aggA, float* aggH, char* lds, int wv) {
;     ...
;             for (int k = 0; k < 4; ++k) { const float zf = (t0 + tok - 3 + k) >= 0 ? 1.f : 0.f; const u32x4 w0 = xw[2 * k], w1 = xw[2 * k + 1];
;                 const float xv[16] = {bflo(w0.x), bfhi(w0.x), bflo(w0.y), bfhi(w0.y), bflo(w0.z), bfhi(w0.z), bflo(w0.w), bfhi(w0.w), bflo(w1.x), bfhi(w1.x), bflo(w1.y), bfhi(w1.y), bflo(w1.z), bfhi(w1.z), bflo(w1.w), bfhi(w1.w)};
; #pragma unroll
;                 for (int i = 0; i < 16; i += 4) { const f32x4 cw = *(const f32x4*)(cwL + k * 64 + cg4 + i) * zf; xc[i] += cw[0] * xv[i]; xc[i + 1] += cw[1] * xv[i + 1]; xc[i + 2] += cw[2] * xv[i + 2]; xc[i + 3] += cw[3] * xv[i + 3]; } }
;             if (j + ns < 256) RNN_LOAD(j + ns);
; #pragma unroll
;             for (int i = 0; i < 16; ++i) xcf[tok * 65 + cg4 + i] = xc[i];
;             u32x4 o0 = {cvtpk(xc[0], xc[1]), cvtpk(xc[2], xc[3]), cvtpk(xc[4], xc[5]), cvtpk(xc[6], xc[7])}, o1 = {cvtpk(xc[8], xc[9]), cvtpk(xc[10], xc[11]), cvtpk(xc[12], xc[13]), cvtpk(xc[14], xc[15])};
;             *(u32x4*)(xcb + tok * 72 + cg4) = o0; *(u32x4*)(xcb + tok * 72 + cg4 + 8) = o1;
;         }
;         LBAR();
;         {
;             const bf16x8 a0 = *(const bf16x8*)(xcb + (wave * 16 + l16) * 72 + q4 * 8), a1 = *(const bf16x8*)(xcb + (wave * 16 + l16) * 72 + 32 + q4 * 8);
; #pragma unroll
;             for (int cg = 0; cg < 4; ++cg) { const int ch = cg * 16 + l16;
;                 f32x4 ca = {0.f, 0.f, 0.f, 0.f}, cx = {0.f, 0.f, 0.f, 0.f};
;                 const bf16x8 wa0 = *(const bf16x8*)(WtL + ch * 72 + q4 * 8), wa1 = *(const bf16x8*)(WtL + ch * 72 + 32 + q4 * 8);
;                 const bf16x8 wx0 = *(const bf16x8*)(WtL + (64 + ch) * 72 + q4 * 8), wx1 = *(const bf16x8*)(WtL + (64 + ch) * 72 + 32 + q4 * 8);
;                 ca = __builtin_amdgcn_mfma_f32_16x16x32_bf16(a0, wa0, ca, 0, 0, 0); ca = __builtin_amdgcn_mfma_f32_16x16x32_bf16(a1, wa1, ca, 0, 0, 0);
;                 cx = __builtin_amdgcn_mfma_f32_16x16x32_bf16(a0, wx0, cx, 0, 0, 0); cx = __builtin_amdgcn_mfma_f32_16x16x32_bf16(a1, wx1, cx, 0, 0, 0);
; #pragma unroll
	v_lshlrev_b32_e32 v46, 16, v47
	v_and_b32_e32 v47, 0xffff0000, v47
	v_pk_mul_f32 v[96:97], v[0:1], v[96:97] op_sel_hi:[0,1]
	v_pk_fma_f32 v[90:91], v[110:111], v[126:127], v[90:91]
	v_lshlrev_b32_e32 v110, 16, v50
	v_and_b32_e32 v111, 0xffff0000, v50
	v_lshlrev_b32_e32 v50, 16, v51
	v_and_b32_e32 v51, 0xffff0000, v51
	v_pk_fma_f32 v[60:61], v[134:135], v[60:61], v[74:75]
	v_lshlrev_b32_e32 v62, 16, v42
	v_and_b32_e32 v63, 0xffff0000, v42
	v_pk_fma_f32 v[46:47], v[136:137], v[46:47], v[76:77]
	v_lshlrev_b32_e32 v42, 16, v43
	v_and_b32_e32 v43, 0xffff0000, v43
	v_pk_fma_f32 v[50:51], v[96:97], v[50:51], v[54:55]
	v_pk_mul_f32 v[54:55], v[0:1], v[88:89] op_sel_hi:[0,1]
	v_lshlrev_b32_e32 v52, 16, v53
	v_and_b32_e32 v53, 0xffff0000, v53
	v_pk_fma_f32 v[60:61], v[118:119], v[62:63], v[60:61]
	v_lshlrev_b32_e32 v62, 16, v38
	v_and_b32_e32 v63, 0xffff0000, v38
	v_pk_fma_f32 v[42:43], v[120:121], v[42:43], v[46:47]
	v_lshlrev_b32_e32 v38, 16, v39
	v_and_b32_e32 v39, 0xffff0000, v39
	v_pk_mul_f32 v[94:95], v[0:1], v[94:95] op_sel_hi:[0,1]
	v_pk_fma_f32 v[52:53], v[54:55], v[52:53], v[56:57]
	v_pk_mul_f32 v[54:55], v[0:1], v[80:81] op_sel_hi:[0,1]
	v_pk_fma_f32 v[60:61], v[102:103], v[62:63], v[60:61]
	v_lshlrev_b32_e32 v62, 16, v34
	v_and_b32_e32 v63, 0xffff0000, v34
	v_pk_fma_f32 v[38:39], v[104:105], v[38:39], v[42:43]
	v_lshlrev_b32_e32 v34, 16, v35
	v_and_b32_e32 v35, 0xffff0000, v35
	v_lshlrev_b32_e32 v46, 16, v48
	v_and_b32_e32 v47, 0xffff0000, v48
	v_pk_fma_f32 v[90:91], v[94:95], v[110:111], v[90:91]
	v_pk_mul_f32 v[56:57], v[0:1], v[78:79] op_sel_hi:[0,1]
	v_pk_fma_f32 v[42:43], v[54:55], v[34:35], v[38:39]
	v_pk_mul_f32 v[34:35], v[0:1], v[72:73] op_sel_hi:[0,1]
	v_pk_mul_f32 v[38:39], v[0:1], v[70:71] op_sel_hi:[0,1]
	v_pk_fma_f32 v[46:47], v[130:131], v[46:47], v[66:67]
	v_lshlrev_b32_e32 v54, 16, v44
	v_and_b32_e32 v55, 0xffff0000, v44
	v_add_u32_e32 v0, 0x4800, v220
	v_pk_fma_f32 v[46:47], v[114:115], v[54:55], v[46:47]
	v_lshlrev_b32_e32 v54, 16, v40
	v_and_b32_e32 v55, 0xffff0000, v40
	ds_write2_b32 v0, v90, v91 offset1:1
	v_add_u32_e32 v0, 0x4808, v220
	v_pk_fma_f32 v[46:47], v[98:99], v[54:55], v[46:47]
	v_lshlrev_b32_e32 v54, 16, v36
	v_and_b32_e32 v55, 0xffff0000, v36
	ds_write2_b32 v0, v50, v51 offset1:1
	v_add_u32_e32 v0, 0x4810, v220
	v_pk_fma_f32 v[46:47], v[38:39], v[54:55], v[46:47]
	v_lshlrev_b32_e32 v38, 16, v49
	v_and_b32_e32 v39, 0xffff0000, v49
	ds_write2_b32 v0, v58, v59 offset1:1
	v_add_u32_e32 v0, 0x4818, v220
	v_pk_fma_f32 v[56:57], v[56:57], v[62:63], v[60:61]
	v_pk_fma_f32 v[38:39], v[132:133], v[38:39], v[68:69]
	v_lshlrev_b32_e32 v44, 16, v45
	v_and_b32_e32 v45, 0xffff0000, v45
	ds_write2_b32 v0, v52, v53 offset1:1
	v_add_u32_e32 v0, 0x4820, v220
	v_pk_fma_f32 v[38:39], v[116:117], v[44:45], v[38:39]
	v_lshlrev_b32_e32 v40, 16, v41
	v_and_b32_e32 v41, 0xffff0000, v41
	ds_write2_b32 v0, v56, v57 offset1:1
	v_add_u32_e32 v0, 0x4828, v220
	v_pk_fma_f32 v[38:39], v[100:101], v[40:41], v[38:39]
	v_lshlrev_b32_e32 v36, 16, v37
	v_and_b32_e32 v37, 0xffff0000, v37
	ds_write2_b32 v0, v42, v43 offset1:1
	v_add_u32_e32 v0, 0x4830, v220
	v_pk_fma_f32 v[44:45], v[34:35], v[36:37], v[38:39]
	ds_write2_b32 v0, v46, v47 offset1:1
	v_add_u32_e32 v0, 0x4838, v220
	ds_write2_b32 v0, v44, v45 offset1:1
	v_cvt_pk_bf16_f32 v34, v90, v91
	v_cvt_pk_bf16_f32 v35, v50, v51
	v_cvt_pk_bf16_f32 v36, v58, v59
	v_cvt_pk_bf16_f32 v37, v52, v53
	v_cvt_pk_bf16_f32 v38, v56, v57
	v_cvt_pk_bf16_f32 v39, v42, v43
	v_cvt_pk_bf16_f32 v40, v46, v47
	v_cvt_pk_bf16_f32 v41, v44, v45
	ds_write_b128 v221, v[34:37]
	ds_write_b128 v221, v[38:41] offset:16
	s_waitcnt lgkmcnt(0)
	s_barrier
	ds_read_b128 v[38:41], v165
	ds_read_b128 v[34:37], v165 offset:64
	ds_read_b128 v[42:45], v168
	ds_read_b128 v[46:49], v168 offset:64
	s_waitcnt lgkmcnt(0)
	v_mfma_f32_16x16x32_bf16 v[42:45], v[38:41], v[42:45], 0
	ds_read_b128 v[50:53], v168 offset:9216
	v_mfma_f32_16x16x32_bf16 v[46:49], v[34:37], v[46:49], v[42:45]
	s_nop 5
	ds_read_b128 v[42:45], v168 offset:9280
	s_waitcnt lgkmcnt(0)
	v_mfma_f32_16x16x32_bf16 v[50:53], v[38:41], v[50:53], 0
	v_add_f32_e32 v0, v149, v46
	v_mul_f32_e32 v0, 0xbfb8aa3b, v0
	v_exp_f32_e32 v0, v0
	v_mfma_f32_16x16x32_bf16 v[42:45], v[34:37], v[42:45], v[50:53]
	v_add_f32_e32 v0, 1.0, v0
	v_rcp_f32_e64 v46, -v0
	ds_read_b32 v0, v169 offset:18432
	v_mul_f32_e32 v46, v158, v46
	v_add_f32_e32 v51, v46, v46
	v_cmp_ngt_f32_e32 vcc, s40, v51
	s_and_saveexec_b64 s[10:11], vcc
	s_xor_b64 s[10:11], exec, s[10:11]
	v_mov_b32_e32 v50, 0x3e2aaaab
	v_fmamk_f32 v50, v51, 0x3d2aaaab, v50
	v_fma_f32 v50, v51, v50, 0.5
	v_fma_f32 v50, v51, v50, 1.0
	v_mul_f32_e64 v50, v50, -v51
	s_or_saveexec_b64 s[10:11], s[10:11]
	v_mul_f32_e32 v46, 0x3fb8aa3b, v46
	v_exp_f32_e32 v46, v46
	s_xor_b64 exec, exec, s[10:11]
	v_fma_f32 v50, -v46, v46, 1.0
	s_or_b64 exec, exec, s[10:11]
	v_add_f32_e32 v42, v152, v42
	v_mul_f32_e32 v42, 0xbfb8aa3b, v42
	v_exp_f32_e32 v42, v42
	v_max_f32_e32 v50, v50, v50
	v_add_f32_e32 v47, v149, v47
	v_max_f32_e32 v50, 0, v50
	v_add_f32_e32 v42, 1.0, v42
	v_rcp_f32_e32 v42, v42
	v_mul_f32_e32 v47, 0xbfb8aa3b, v47
	v_sqrt_f32_e32 v50, v50
	v_exp_f32_e32 v47, v47
	s_waitcnt lgkmcnt(0)
; DEVI float sigmoidf_(float x) { return __builtin_amdgcn_rcpf(1.f + __expf(-x)); }
; DEVI void rnn_local_phase(const bf16_t* xr, const float* convw, const float* convb, const bf16_t* lruT, const float* ba, const float* bx, const float* lam,
;                           bf16_t* hloc, bf16_t* pcum, float* aggA, float* aggH, char* lds, int wv) {
;     ...
;             for (int cg = 0; cg < 4; ++cg) { const int ch = cg * 16 + l16;
;                 f32x4 ca = {0.f, 0.f, 0.f, 0.f}, cx = {0.f, 0.f, 0.f, 0.f};
;                 const bf16x8 wa0 = *(const bf16x8*)(WtL + ch * 72 + q4 * 8), wa1 = *(const bf16x8*)(WtL + ch * 72 + 32 + q4 * 8);
;                 const bf16x8 wx0 = *(const bf16x8*)(WtL + (64 + ch) * 72 + q4 * 8), wx1 = *(const bf16x8*)(WtL + (64 + ch) * 72 + 32 + q4 * 8);
;                 ca = __builtin_amdgcn_mfma_f32_16x16x32_bf16(a0, wa0, ca, 0, 0, 0); ca = __builtin_amdgcn_mfma_f32_16x16x32_bf16(a1, wa1, ca, 0, 0, 0);
;                 cx = __builtin_amdgcn_mfma_f32_16x16x32_bf16(a0, wx0, cx, 0, 0, 0); cx = __builtin_amdgcn_mfma_f32_16x16x32_bf16(a1, wx1, cx, 0, 0, 0);
; #pragma unroll
;                 for (int i = 0; i < 4; ++i) { const int tk = wave * 16 + q4 * 4 + i; const float xv = xcf[tk * 65 + ch];
;                     const float r = sigmoidf_(ca[i] + bav[cg]), ig = sigmoidf_(cx[i] + bxv[cg]), la = -r * sp8[cg], a = __expf(la);
;                     const float y2 = 2.f * la; const float om = y2 < -0.05f ? 1.f - a * a : -y2 * (1.f + y2 * (0.5f + y2 * (0.16666667f + y2 * 0.041666668f)));
;                     const float u = __builtin_amdgcn_sqrtf(fmaxf(om, 0.f)) * (ig * xv);
;                     aL[tk * 65 + ch] = a; uL[tk * 65 + ch] = u; } }
	v_mul_f32_e32 v0, v0, v42
	ds_write_b32 v169, v46 offset:51712
	v_mul_f32_e32 v42, v0, v50
	v_add_f32_e32 v0, 1.0, v47
	v_rcp_f32_e64 v47, -v0
	ds_read_b32 v0, v169 offset:18692
	ds_write_b32 v170, v42
	v_mul_f32_e32 v42, v158, v47
	v_add_f32_e32 v47, v42, v42
	v_cmp_ngt_f32_e32 vcc, s40, v47
	s_and_saveexec_b64 s[10:11], vcc
	s_xor_b64 s[10:11], exec, s[10:11]
	v_mov_b32_e32 v46, 0x3e2aaaab
	v_fmamk_f32 v46, v47, 0x3d2aaaab, v46
	v_fma_f32 v46, v47, v46, 0.5
	v_fma_f32 v46, v47, v46, 1.0
	v_mul_f32_e64 v46, v46, -v47
	s_or_saveexec_b64 s[10:11], s[10:11]
	v_mul_f32_e32 v42, 0x3fb8aa3b, v42
	v_exp_f32_e32 v42, v42
	s_xor_b64 exec, exec, s[10:11]
	v_fma_f32 v46, -v42, v42, 1.0
	s_or_b64 exec, exec, s[10:11]
	v_add_f32_e32 v43, v152, v43
	v_mul_f32_e32 v43, 0xbfb8aa3b, v43
	v_exp_f32_e32 v43, v43
	v_add_f32_e32 v47, v149, v48
	v_max_f32_e32 v46, v46, v46
	v_mul_f32_e32 v47, 0xbfb8aa3b, v47
	v_add_f32_e32 v43, 1.0, v43
	v_max_f32_e32 v46, 0, v46
	v_rcp_f32_e32 v43, v43
	v_exp_f32_e32 v47, v47
	v_sqrt_f32_e32 v46, v46
	ds_write_b32 v169, v42 offset:51972
	s_waitcnt lgkmcnt(0)
	v_mul_f32_e32 v0, v43, v0
	v_add_f32_e32 v42, 1.0, v47
	v_mul_f32_e32 v0, v0, v46
	v_rcp_f32_e64 v42, -v42
	ds_write_b32 v171, v0
	ds_read_b32 v0, v169 offset:18952
	v_mul_f32_e32 v42, v158, v42
	v_add_f32_e32 v46, v42, v42
	v_cmp_ngt_f32_e32 vcc, s40, v46
	s_and_saveexec_b64 s[10:11], vcc
	s_xor_b64 s[10:11], exec, s[10:11]
	v_mov_b32_e32 v43, 0x3e2aaaab
	v_fmamk_f32 v43, v46, 0x3d2aaaab, v43
	v_fma_f32 v43, v46, v43, 0.5
	v_fma_f32 v43, v46, v43, 1.0
	v_mul_f32_e64 v43, v43, -v46
	s_or_saveexec_b64 s[10:11], s[10:11]
	v_mul_f32_e32 v42, 0x3fb8aa3b, v42
	v_exp_f32_e32 v42, v42
	s_xor_b64 exec, exec, s[10:11]
	v_fma_f32 v43, -v42, v42, 1.0
	s_or_b64 exec, exec, s[10:11]
	v_add_f32_e32 v44, v152, v44
	v_mul_f32_e32 v44, 0xbfb8aa3b, v44
	v_exp_f32_e32 v44, v44
	v_add_f32_e32 v46, v149, v49
	v_max_f32_e32 v43, v43, v43
	v_mul_f32_e32 v46, 0xbfb8aa3b, v46
	v_add_f32_e32 v44, 1.0, v44
	v_max_f32_e32 v43, 0, v43
	v_rcp_f32_e32 v44, v44
	v_exp_f32_e32 v46, v46
	v_sqrt_f32_e32 v43, v43
	ds_write_b32 v169, v42 offset:52232
	s_waitcnt lgkmcnt(0)
	v_mul_f32_e32 v0, v44, v0
	v_add_f32_e32 v42, 1.0, v46
	v_mul_f32_e32 v0, v0, v43
	v_rcp_f32_e64 v42, -v42
	ds_write_b32 v172, v0
	ds_read_b32 v0, v169 offset:19212
	v_mul_f32_e32 v43, v158, v42
	v_add_f32_e32 v44, v43, v43
	v_cmp_ngt_f32_e32 vcc, s40, v44
	s_and_saveexec_b64 s[10:11], vcc
	s_xor_b64 s[10:11], exec, s[10:11]
	v_mov_b32_e32 v42, 0x3e2aaaab
	v_fmamk_f32 v42, v44, 0x3d2aaaab, v42
	v_fma_f32 v42, v44, v42, 0.5
	v_fma_f32 v42, v44, v42, 1.0
	v_mul_f32_e64 v42, v42, -v44
	s_or_saveexec_b64 s[10:11], s[10:11]
	v_mul_f32_e32 v43, 0x3fb8aa3b, v43
	v_exp_f32_e32 v43, v43
	s_xor_b64 exec, exec, s[10:11]
	v_fma_f32 v42, -v43, v43, 1.0
	s_or_b64 exec, exec, s[10:11]
	v_add_f32_e32 v44, v152, v45
	v_mul_f32_e32 v44, 0xbfb8aa3b, v44
	v_exp_f32_e32 v44, v44
	v_max_f32_e32 v42, v42, v42
	v_max_f32_e32 v42, 0, v42
	v_sqrt_f32_e32 v42, v42
	v_add_f32_e32 v44, 1.0, v44
	v_rcp_f32_e32 v44, v44
	ds_write_b32 v169, v43 offset:52492
	s_waitcnt lgkmcnt(0)
	v_mul_f32_e32 v0, v44, v0
	v_mul_f32_e32 v0, v0, v42
	ds_write_b32 v173, v0
	ds_read_b128 v[42:45], v174
	ds_read_b32 v0, v169 offset:18496
	ds_read_b128 v[46:49], v174 offset:64
	ds_read_b128 v[50:53], v174 offset:9216
	s_waitcnt lgkmcnt(0)
	v_mfma_f32_16x16x32_bf16 v[42:45], v[38:41], v[42:45], 0
	v_mfma_f32_16x16x32_bf16 v[46:49], v[34:37], v[46:49], v[42:45]
	v_mfma_f32_16x16x32_bf16 v[50:53], v[38:41], v[50:53], 0
	s_nop 6
	v_add_f32_e32 v42, v150, v46
	v_mul_f32_e32 v42, 0xbfb8aa3b, v42
	v_exp_f32_e32 v46, v42
	ds_read_b128 v[42:45], v174 offset:9280
	s_waitcnt lgkmcnt(0)
	v_mfma_f32_16x16x32_bf16 v[42:45], v[34:37], v[42:45], v[50:53]
	v_add_f32_e32 v46, 1.0, v46
	v_rcp_f32_e64 v46, -v46
	s_nop 0
	v_mul_f32_e32 v46, v159, v46
	v_add_f32_e32 v51, v46, v46
	v_cmp_ngt_f32_e32 vcc, s40, v51
	s_and_saveexec_b64 s[10:11], vcc
	s_xor_b64 s[10:11], exec, s[10:11]
	v_mov_b32_e32 v50, 0x3e2aaaab
	v_fmamk_f32 v50, v51, 0x3d2aaaab, v50
	v_fma_f32 v50, v51, v50, 0.5
	v_fma_f32 v50, v51, v50, 1.0
	v_mul_f32_e64 v50, v50, -v51
	s_or_saveexec_b64 s[10:11], s[10:11]
	v_mul_f32_e32 v46, 0x3fb8aa3b, v46
	v_exp_f32_e32 v46, v46
	s_xor_b64 exec, exec, s[10:11]
	v_fma_f32 v50, -v46, v46, 1.0
	s_or_b64 exec, exec, s[10:11]
	v_add_f32_e32 v42, v153, v42
	v_mul_f32_e32 v42, 0xbfb8aa3b, v42
	v_exp_f32_e32 v42, v42
	v_max_f32_e32 v50, v50, v50
	v_add_f32_e32 v47, v150, v47
	v_max_f32_e32 v50, 0, v50
	v_add_f32_e32 v42, 1.0, v42
	v_rcp_f32_e32 v42, v42
	v_mul_f32_e32 v47, 0xbfb8aa3b, v47
	v_sqrt_f32_e32 v50, v50
	v_exp_f32_e32 v47, v47
	v_mul_f32_e32 v0, v0, v42
	ds_write_b32 v169, v46 offset:51776
	v_mul_f32_e32 v42, v0, v50
	v_add_f32_e32 v0, 1.0, v47
	v_rcp_f32_e64 v47, -v0
	ds_read_b32 v0, v176 offset:18692
	ds_write_b32 v175, v42
	v_mul_f32_e32 v42, v159, v47
	v_add_f32_e32 v47, v42, v42
	v_cmp_ngt_f32_e32 vcc, s40, v47
	s_and_saveexec_b64 s[10:11], vcc
	s_xor_b64 s[10:11], exec, s[10:11]
	v_mov_b32_e32 v46, 0x3e2aaaab
	v_fmamk_f32 v46, v47, 0x3d2aaaab, v46
	v_fma_f32 v46, v47, v46, 0.5
	v_fma_f32 v46, v47, v46, 1.0
	v_mul_f32_e64 v46, v46, -v47
	s_or_saveexec_b64 s[10:11], s[10:11]
	v_mul_f32_e32 v42, 0x3fb8aa3b, v42
	v_exp_f32_e32 v42, v42
	s_xor_b64 exec, exec, s[10:11]
	v_fma_f32 v46, -v42, v42, 1.0
	s_or_b64 exec, exec, s[10:11]
	v_add_f32_e32 v43, v153, v43
	v_mul_f32_e32 v43, 0xbfb8aa3b, v43
	v_exp_f32_e32 v43, v43
	v_add_f32_e32 v47, v150, v48
	v_max_f32_e32 v46, v46, v46
	v_mul_f32_e32 v47, 0xbfb8aa3b, v47
	v_add_f32_e32 v43, 1.0, v43
	v_max_f32_e32 v46, 0, v46
	v_rcp_f32_e32 v43, v43
	v_exp_f32_e32 v47, v47
	v_sqrt_f32_e32 v46, v46
	ds_write_b32 v176, v42 offset:51972
	s_waitcnt lgkmcnt(0)
; DEVI float sigmoidf_(float x) { return __builtin_amdgcn_rcpf(1.f + __expf(-x)); }
; DEVI void rnn_local_phase(const bf16_t* xr, const float* convw, const float* convb, const bf16_t* lruT, const float* ba, const float* bx, const float* lam,
;                           bf16_t* hloc, bf16_t* pcum, float* aggA, float* aggH, char* lds, int wv) {
;     ...
;             for (int cg = 0; cg < 4; ++cg) { const int ch = cg * 16 + l16;
;                 f32x4 ca = {0.f, 0.f, 0.f, 0.f}, cx = {0.f, 0.f, 0.f, 0.f};
;                 const bf16x8 wa0 = *(const bf16x8*)(WtL + ch * 72 + q4 * 8), wa1 = *(const bf16x8*)(WtL + ch * 72 + 32 + q4 * 8);
;                 const bf16x8 wx0 = *(const bf16x8*)(WtL + (64 + ch) * 72 + q4 * 8), wx1 = *(const bf16x8*)(WtL + (64 + ch) * 72 + 32 + q4 * 8);
;                 ca = __builtin_amdgcn_mfma_f32_16x16x32_bf16(a0, wa0, ca, 0, 0, 0); ca = __builtin_amdgcn_mfma_f32_16x16x32_bf16(a1, wa1, ca, 0, 0, 0);
;                 cx = __builtin_amdgcn_mfma_f32_16x16x32_bf16(a0, wx0, cx, 0, 0, 0); cx = __builtin_amdgcn_mfma_f32_16x16x32_bf16(a1, wx1, cx, 0, 0, 0);
; #pragma unroll
;                 for (int i = 0; i < 4; ++i) { const int tk = wave * 16 + q4 * 4 + i; const float xv = xcf[tk * 65 + ch];
;                     const float r = sigmoidf_(ca[i] + bav[cg]), ig = sigmoidf_(cx[i] + bxv[cg]), la = -r * sp8[cg], a = __expf(la);
;                     const float y2 = 2.f * la; const float om = y2 < -0.05f ? 1.f - a * a : -y2 * (1.f + y2 * (0.5f + y2 * (0.16666667f + y2 * 0.041666668f)));
;                     const float u = __builtin_amdgcn_sqrtf(fmaxf(om, 0.f)) * (ig * xv);
;                     aL[tk * 65 + ch] = a; uL[tk * 65 + ch] = u; } }
	v_mul_f32_e32 v0, v43, v0
	v_add_f32_e32 v42, 1.0, v47
	v_mul_f32_e32 v0, v0, v46
	v_rcp_f32_e64 v42, -v42
	ds_write_b32 v177, v0
	ds_read_b32 v0, v176 offset:18952
	v_mul_f32_e32 v42, v159, v42
	v_add_f32_e32 v46, v42, v42
	v_cmp_ngt_f32_e32 vcc, s40, v46
	s_and_saveexec_b64 s[10:11], vcc
	s_xor_b64 s[10:11], exec, s[10:11]
	v_mov_b32_e32 v43, 0x3e2aaaab
	v_fmamk_f32 v43, v46, 0x3d2aaaab, v43
	v_fma_f32 v43, v46, v43, 0.5
	v_fma_f32 v43, v46, v43, 1.0
	v_mul_f32_e64 v43, v43, -v46
	s_or_saveexec_b64 s[10:11], s[10:11]
	v_mul_f32_e32 v42, 0x3fb8aa3b, v42
	v_exp_f32_e32 v42, v42
	s_xor_b64 exec, exec, s[10:11]
	v_fma_f32 v43, -v42, v42, 1.0
	s_or_b64 exec, exec, s[10:11]
	v_add_f32_e32 v44, v153, v44
	v_mul_f32_e32 v44, 0xbfb8aa3b, v44
	v_exp_f32_e32 v44, v44
	v_add_f32_e32 v46, v150, v49
	v_max_f32_e32 v43, v43, v43
	v_mul_f32_e32 v46, 0xbfb8aa3b, v46
	v_add_f32_e32 v44, 1.0, v44
	v_max_f32_e32 v43, 0, v43
	v_rcp_f32_e32 v44, v44
	v_exp_f32_e32 v46, v46
	v_sqrt_f32_e32 v43, v43
	ds_write_b32 v176, v42 offset:52232
	s_waitcnt lgkmcnt(0)
	v_mul_f32_e32 v0, v44, v0
	v_add_f32_e32 v42, 1.0, v46
	v_mul_f32_e32 v0, v0, v43
	v_rcp_f32_e64 v42, -v42
	ds_write_b32 v178, v0
	ds_read_b32 v0, v176 offset:19212
	v_mul_f32_e32 v43, v159, v42
	v_add_f32_e32 v44, v43, v43
	v_cmp_ngt_f32_e32 vcc, s40, v44
	s_and_saveexec_b64 s[10:11], vcc
	s_xor_b64 s[10:11], exec, s[10:11]
	v_mov_b32_e32 v42, 0x3e2aaaab
	v_fmamk_f32 v42, v44, 0x3d2aaaab, v42
	v_fma_f32 v42, v44, v42, 0.5
	v_fma_f32 v42, v44, v42, 1.0
	v_mul_f32_e64 v42, v42, -v44
	s_or_saveexec_b64 s[10:11], s[10:11]
	v_mul_f32_e32 v43, 0x3fb8aa3b, v43
	v_exp_f32_e32 v43, v43
	s_xor_b64 exec, exec, s[10:11]
	v_fma_f32 v42, -v43, v43, 1.0
	s_or_b64 exec, exec, s[10:11]
	v_add_f32_e32 v44, v153, v45
	v_mul_f32_e32 v44, 0xbfb8aa3b, v44
	v_exp_f32_e32 v44, v44
	v_max_f32_e32 v42, v42, v42
	v_max_f32_e32 v42, 0, v42
	v_sqrt_f32_e32 v42, v42
	v_add_f32_e32 v44, 1.0, v44
	v_rcp_f32_e32 v44, v44
	ds_write_b32 v176, v43 offset:52492
	s_waitcnt lgkmcnt(0)
	v_mul_f32_e32 v0, v44, v0
	v_mul_f32_e32 v0, v0, v42
	ds_write_b32 v179, v0
	ds_read_b128 v[42:45], v180
	ds_read_b32 v0, v169 offset:18560
	ds_read_b128 v[46:49], v180 offset:64
	ds_read_b128 v[50:53], v180 offset:9216
	s_waitcnt lgkmcnt(0)
	v_mfma_f32_16x16x32_bf16 v[42:45], v[38:41], v[42:45], 0
	v_mfma_f32_16x16x32_bf16 v[46:49], v[34:37], v[46:49], v[42:45]
	v_mfma_f32_16x16x32_bf16 v[50:53], v[38:41], v[50:53], 0
	s_nop 6
	v_add_f32_e32 v42, v151, v46
	v_mul_f32_e32 v42, 0xbfb8aa3b, v42
	v_exp_f32_e32 v46, v42
	ds_read_b128 v[42:45], v180 offset:9280
	s_waitcnt lgkmcnt(0)
	v_mfma_f32_16x16x32_bf16 v[42:45], v[34:37], v[42:45], v[50:53]
	v_add_f32_e32 v46, 1.0, v46
	v_rcp_f32_e64 v46, -v46
	s_nop 0
	v_mul_f32_e32 v46, v160, v46
	v_add_f32_e32 v51, v46, v46
	v_cmp_ngt_f32_e32 vcc, s40, v51
	s_and_saveexec_b64 s[10:11], vcc
	s_xor_b64 s[10:11], exec, s[10:11]
	v_mov_b32_e32 v50, 0x3e2aaaab
	v_fmamk_f32 v50, v51, 0x3d2aaaab, v50
	v_fma_f32 v50, v51, v50, 0.5
	v_fma_f32 v50, v51, v50, 1.0
	v_mul_f32_e64 v50, v50, -v51
	s_or_saveexec_b64 s[10:11], s[10:11]
	v_mul_f32_e32 v46, 0x3fb8aa3b, v46
	v_exp_f32_e32 v46, v46
	s_xor_b64 exec, exec, s[10:11]
	v_fma_f32 v50, -v46, v46, 1.0
	s_or_b64 exec, exec, s[10:11]
	v_add_f32_e32 v42, v154, v42
	v_mul_f32_e32 v42, 0xbfb8aa3b, v42
	v_exp_f32_e32 v42, v42
	v_max_f32_e32 v50, v50, v50
	v_add_f32_e32 v47, v151, v47
	v_max_f32_e32 v50, 0, v50
	v_add_f32_e32 v42, 1.0, v42
	v_rcp_f32_e32 v42, v42
	v_mul_f32_e32 v47, 0xbfb8aa3b, v47
	v_sqrt_f32_e32 v50, v50
	v_exp_f32_e32 v47, v47
	v_mul_f32_e32 v0, v0, v42
	ds_write_b32 v169, v46 offset:51840
	v_mul_f32_e32 v42, v0, v50
	v_add_f32_e32 v0, 1.0, v47
	v_rcp_f32_e64 v47, -v0
	ds_read_b32 v0, v182 offset:18692
	ds_write_b32 v181, v42
	v_mul_f32_e32 v42, v160, v47
	v_add_f32_e32 v47, v42, v42
	v_cmp_ngt_f32_e32 vcc, s40, v47
	s_and_saveexec_b64 s[10:11], vcc
	s_xor_b64 s[10:11], exec, s[10:11]
	v_mov_b32_e32 v46, 0x3e2aaaab
	v_fmamk_f32 v46, v47, 0x3d2aaaab, v46
	v_fma_f32 v46, v47, v46, 0.5
	v_fma_f32 v46, v47, v46, 1.0
	v_mul_f32_e64 v46, v46, -v47
	s_or_saveexec_b64 s[10:11], s[10:11]
	v_mul_f32_e32 v42, 0x3fb8aa3b, v42
	v_exp_f32_e32 v42, v42
	s_xor_b64 exec, exec, s[10:11]
	v_fma_f32 v46, -v42, v42, 1.0
	s_or_b64 exec, exec, s[10:11]
	v_add_f32_e32 v43, v154, v43
	v_mul_f32_e32 v43, 0xbfb8aa3b, v43
	v_exp_f32_e32 v43, v43
	v_add_f32_e32 v47, v151, v48
	v_max_f32_e32 v46, v46, v46
	v_mul_f32_e32 v47, 0xbfb8aa3b, v47
	v_add_f32_e32 v43, 1.0, v43
	v_max_f32_e32 v46, 0, v46
	v_rcp_f32_e32 v43, v43
	v_exp_f32_e32 v47, v47
	v_sqrt_f32_e32 v46, v46
	ds_write_b32 v182, v42 offset:51972
	s_waitcnt lgkmcnt(0)
	v_mul_f32_e32 v0, v43, v0
	v_add_f32_e32 v42, 1.0, v47
	v_mul_f32_e32 v0, v0, v46
	v_rcp_f32_e64 v42, -v42
	ds_write_b32 v183, v0
	ds_read_b32 v0, v182 offset:18952
	v_mul_f32_e32 v42, v160, v42
	v_add_f32_e32 v46, v42, v42
	v_cmp_ngt_f32_e32 vcc, s40, v46
	s_and_saveexec_b64 s[10:11], vcc
	s_xor_b64 s[10:11], exec, s[10:11]
	v_mov_b32_e32 v43, 0x3e2aaaab
	v_fmamk_f32 v43, v46, 0x3d2aaaab, v43
	v_fma_f32 v43, v46, v43, 0.5
	v_fma_f32 v43, v46, v43, 1.0
	v_mul_f32_e64 v43, v43, -v46
	s_or_saveexec_b64 s[10:11], s[10:11]
	v_mul_f32_e32 v42, 0x3fb8aa3b, v42
	v_exp_f32_e32 v42, v42
	s_xor_b64 exec, exec, s[10:11]
	v_fma_f32 v43, -v42, v42, 1.0
	s_or_b64 exec, exec, s[10:11]
	v_add_f32_e32 v44, v154, v44
	v_mul_f32_e32 v44, 0xbfb8aa3b, v44
	v_exp_f32_e32 v44, v44
	v_add_f32_e32 v46, v151, v49
	v_max_f32_e32 v43, v43, v43
	v_mul_f32_e32 v46, 0xbfb8aa3b, v46
	v_add_f32_e32 v44, 1.0, v44
	v_max_f32_e32 v43, 0, v43
	v_rcp_f32_e32 v44, v44
	v_exp_f32_e32 v46, v46
	v_sqrt_f32_e32 v43, v43
	ds_write_b32 v182, v42 offset:52232
	s_waitcnt lgkmcnt(0)
; DEVI float sigmoidf_(float x) { return __builtin_amdgcn_rcpf(1.f + __expf(-x)); }
; #define LBAR() do { asm volatile("s_waitcnt lgkmcnt(0)" ::: "memory"); __builtin_amdgcn_s_barrier(); asm volatile("" ::: "memory"); } while (0)
; DEVI void rnn_local_phase(const bf16_t* xr, const float* convw, const float* convb, const bf16_t* lruT, const float* ba, const float* bx, const float* lam,
;                           bf16_t* hloc, bf16_t* pcum, float* aggA, float* aggH, char* lds, int wv) {
;     ...
;             for (int cg = 0; cg < 4; ++cg) { const int ch = cg * 16 + l16;
;                 f32x4 ca = {0.f, 0.f, 0.f, 0.f}, cx = {0.f, 0.f, 0.f, 0.f};
;                 const bf16x8 wa0 = *(const bf16x8*)(WtL + ch * 72 + q4 * 8), wa1 = *(const bf16x8*)(WtL + ch * 72 + 32 + q4 * 8);
;                 const bf16x8 wx0 = *(const bf16x8*)(WtL + (64 + ch) * 72 + q4 * 8), wx1 = *(const bf16x8*)(WtL + (64 + ch) * 72 + 32 + q4 * 8);
;                 ca = __builtin_amdgcn_mfma_f32_16x16x32_bf16(a0, wa0, ca, 0, 0, 0); ca = __builtin_amdgcn_mfma_f32_16x16x32_bf16(a1, wa1, ca, 0, 0, 0);
;                 cx = __builtin_amdgcn_mfma_f32_16x16x32_bf16(a0, wx0, cx, 0, 0, 0); cx = __builtin_amdgcn_mfma_f32_16x16x32_bf16(a1, wx1, cx, 0, 0, 0);
; #pragma unroll
;                 for (int i = 0; i < 4; ++i) { const int tk = wave * 16 + q4 * 4 + i; const float xv = xcf[tk * 65 + ch];
;                     const float r = sigmoidf_(ca[i] + bav[cg]), ig = sigmoidf_(cx[i] + bxv[cg]), la = -r * sp8[cg], a = __expf(la);
;                     const float y2 = 2.f * la; const float om = y2 < -0.05f ? 1.f - a * a : -y2 * (1.f + y2 * (0.5f + y2 * (0.16666667f + y2 * 0.041666668f)));
;                     const float u = __builtin_amdgcn_sqrtf(fmaxf(om, 0.f)) * (ig * xv);
;                     aL[tk * 65 + ch] = a; uL[tk * 65 + ch] = u; } }
;         }
;         LBAR();
	v_mul_f32_e32 v0, v44, v0
	v_add_f32_e32 v42, 1.0, v46
	v_mul_f32_e32 v0, v0, v43
	v_rcp_f32_e64 v42, -v42
	ds_write_b32 v184, v0
	ds_read_b32 v0, v182 offset:19212
	v_mul_f32_e32 v43, v160, v42
	v_add_f32_e32 v44, v43, v43
	v_cmp_ngt_f32_e32 vcc, s40, v44
	s_and_saveexec_b64 s[10:11], vcc
	s_xor_b64 s[10:11], exec, s[10:11]
	v_mov_b32_e32 v42, 0x3e2aaaab
	v_fmamk_f32 v42, v44, 0x3d2aaaab, v42
	v_fma_f32 v42, v44, v42, 0.5
	v_fma_f32 v42, v44, v42, 1.0
	v_mul_f32_e64 v42, v42, -v44
	s_or_saveexec_b64 s[10:11], s[10:11]
	v_mul_f32_e32 v43, 0x3fb8aa3b, v43
	v_exp_f32_e32 v43, v43
	s_xor_b64 exec, exec, s[10:11]
	v_fma_f32 v42, -v43, v43, 1.0
	s_or_b64 exec, exec, s[10:11]
	v_add_f32_e32 v44, v154, v45
	v_mul_f32_e32 v44, 0xbfb8aa3b, v44
	v_exp_f32_e32 v44, v44
	v_max_f32_e32 v42, v42, v42
	v_max_f32_e32 v42, 0, v42
	v_sqrt_f32_e32 v42, v42
	v_add_f32_e32 v44, 1.0, v44
	v_rcp_f32_e32 v44, v44
	ds_write_b32 v182, v43 offset:52492
	s_waitcnt lgkmcnt(0)
	v_mul_f32_e32 v0, v44, v0
	v_mul_f32_e32 v0, v0, v42
	ds_write_b32 v185, v0
	ds_read_b128 v[42:45], v186
	ds_read_b128 v[46:49], v186 offset:64
	ds_read_b128 v[50:53], v186 offset:9216
	s_waitcnt lgkmcnt(0)
	v_mfma_f32_16x16x32_bf16 v[42:45], v[38:41], v[42:45], 0
	v_mfma_f32_16x16x32_bf16 v[42:45], v[34:37], v[46:49], v[42:45]
	ds_read_b128 v[46:49], v186 offset:9280
	v_mfma_f32_16x16x32_bf16 v[38:41], v[38:41], v[50:53], 0
	s_nop 5
	v_add_f32_e32 v0, v156, v42
	v_mul_f32_e32 v0, 0xbfb8aa3b, v0
	v_exp_f32_e32 v0, v0
	s_nop 0
	v_add_f32_e32 v0, 1.0, v0
	v_rcp_f32_e64 v42, -v0
	ds_read_b32 v0, v169 offset:18624
	s_waitcnt lgkmcnt(0)
	v_mfma_f32_16x16x32_bf16 v[34:37], v[34:37], v[46:49], v[38:41]
	s_nop 2
	v_mul_f32_e32 v38, v161, v42
	v_add_f32_e32 v40, v38, v38
	v_cmp_ngt_f32_e32 vcc, s40, v40
	s_and_saveexec_b64 s[10:11], vcc
	s_xor_b64 s[10:11], exec, s[10:11]
	v_mov_b32_e32 v39, 0x3e2aaaab
	v_fmamk_f32 v39, v40, 0x3d2aaaab, v39
	v_fma_f32 v39, v40, v39, 0.5
	v_fma_f32 v39, v40, v39, 1.0
	v_mul_f32_e64 v39, v39, -v40
	s_or_saveexec_b64 s[10:11], s[10:11]
	v_mul_f32_e32 v38, 0x3fb8aa3b, v38
	v_exp_f32_e32 v38, v38
	s_xor_b64 exec, exec, s[10:11]
	v_fma_f32 v39, -v38, v38, 1.0
	s_or_b64 exec, exec, s[10:11]
	v_add_f32_e32 v34, v155, v34
	v_mul_f32_e32 v34, 0xbfb8aa3b, v34
	v_exp_f32_e32 v34, v34
	v_max_f32_e32 v39, v39, v39
	v_add_f32_e32 v40, v156, v43
	v_max_f32_e32 v39, 0, v39
	v_add_f32_e32 v34, 1.0, v34
	v_rcp_f32_e32 v34, v34
	v_mul_f32_e32 v40, 0xbfb8aa3b, v40
	v_sqrt_f32_e32 v39, v39
	v_exp_f32_e32 v40, v40
	v_mul_f32_e32 v0, v0, v34
	ds_write_b32 v169, v38 offset:51904
	v_mul_f32_e32 v34, v0, v39
	v_add_f32_e32 v0, 1.0, v40
	v_rcp_f32_e64 v39, -v0
	ds_read_b32 v0, v188 offset:18692
	ds_write_b32 v187, v34
	v_mul_f32_e32 v34, v161, v39
	v_add_f32_e32 v39, v34, v34
	v_cmp_ngt_f32_e32 vcc, s40, v39
	s_and_saveexec_b64 s[10:11], vcc
	s_xor_b64 s[10:11], exec, s[10:11]
	v_mov_b32_e32 v38, 0x3e2aaaab
	v_fmamk_f32 v38, v39, 0x3d2aaaab, v38
	v_fma_f32 v38, v39, v38, 0.5
	v_fma_f32 v38, v39, v38, 1.0
	v_mul_f32_e64 v38, v38, -v39
	s_or_saveexec_b64 s[10:11], s[10:11]
	v_mul_f32_e32 v34, 0x3fb8aa3b, v34
	v_exp_f32_e32 v34, v34
	s_xor_b64 exec, exec, s[10:11]
	v_fma_f32 v38, -v34, v34, 1.0
	s_or_b64 exec, exec, s[10:11]
	v_add_f32_e32 v35, v155, v35
	v_mul_f32_e32 v35, 0xbfb8aa3b, v35
	v_exp_f32_e32 v35, v35
	v_add_f32_e32 v39, v156, v44
	v_max_f32_e32 v38, v38, v38
	v_mul_f32_e32 v39, 0xbfb8aa3b, v39
	v_add_f32_e32 v35, 1.0, v35
	v_max_f32_e32 v38, 0, v38
	v_rcp_f32_e32 v35, v35
	v_exp_f32_e32 v39, v39
	v_sqrt_f32_e32 v38, v38
	ds_write_b32 v188, v34 offset:51972
	s_waitcnt lgkmcnt(0)
	v_mul_f32_e32 v0, v35, v0
	v_add_f32_e32 v34, 1.0, v39
	v_mul_f32_e32 v0, v0, v38
	v_rcp_f32_e64 v34, -v34
	ds_write_b32 v189, v0
	ds_read_b32 v0, v188 offset:18952
	v_mul_f32_e32 v34, v161, v34
	v_add_f32_e32 v38, v34, v34
	v_cmp_ngt_f32_e32 vcc, s40, v38
	s_and_saveexec_b64 s[10:11], vcc
	s_xor_b64 s[10:11], exec, s[10:11]
	v_mov_b32_e32 v35, 0x3e2aaaab
	v_fmamk_f32 v35, v38, 0x3d2aaaab, v35
	v_fma_f32 v35, v38, v35, 0.5
	v_fma_f32 v35, v38, v35, 1.0
	v_mul_f32_e64 v35, v35, -v38
	s_or_saveexec_b64 s[10:11], s[10:11]
	v_mul_f32_e32 v34, 0x3fb8aa3b, v34
	v_exp_f32_e32 v34, v34
	s_xor_b64 exec, exec, s[10:11]
	v_fma_f32 v35, -v34, v34, 1.0
	s_or_b64 exec, exec, s[10:11]
	v_add_f32_e32 v36, v155, v36
	v_mul_f32_e32 v36, 0xbfb8aa3b, v36
	v_exp_f32_e32 v36, v36
	v_add_f32_e32 v38, v156, v45
	v_max_f32_e32 v35, v35, v35
	v_mul_f32_e32 v38, 0xbfb8aa3b, v38
	v_add_f32_e32 v36, 1.0, v36
	v_max_f32_e32 v35, 0, v35
	v_rcp_f32_e32 v36, v36
	v_exp_f32_e32 v38, v38
	v_sqrt_f32_e32 v35, v35
	ds_write_b32 v188, v34 offset:52232
	s_waitcnt lgkmcnt(0)
	v_mul_f32_e32 v0, v36, v0
	v_add_f32_e32 v34, 1.0, v38
	v_mul_f32_e32 v0, v0, v35
	v_rcp_f32_e64 v35, -v34
	ds_write_b32 v190, v0
	ds_read_b32 v34, v188 offset:19212
	v_mul_f32_e32 v0, v161, v35
	v_add_f32_e32 v35, v0, v0
	v_cmp_ngt_f32_e32 vcc, s40, v35
	s_and_saveexec_b64 s[10:11], vcc
	s_xor_b64 s[10:11], exec, s[10:11]
	v_mov_b32_e32 v36, 0x3e2aaaab
	v_fmamk_f32 v36, v35, 0x3d2aaaab, v36
	v_fma_f32 v36, v35, v36, 0.5
	v_fma_f32 v36, v35, v36, 1.0
	v_mul_f32_e64 v36, v36, -v35
	s_or_saveexec_b64 s[10:11], s[10:11]
	v_mul_f32_e32 v0, 0x3fb8aa3b, v0
	v_exp_f32_e32 v35, v0
	s_xor_b64 exec, exec, s[10:11]
	v_fma_f32 v36, -v35, v35, 1.0
	s_or_b64 exec, exec, s[10:11]
	v_add_f32_e32 v0, v155, v37
	v_mul_f32_e32 v0, 0xbfb8aa3b, v0
	v_exp_f32_e32 v37, v0
	v_max_f32_e32 v38, v36, v36
	v_max_f32_e32 v38, 0, v38
	v_sqrt_f32_e32 v38, v38
	v_add_f32_e32 v37, 1.0, v37
	v_rcp_f32_e32 v37, v37
	v_add_u32_e32 v39, 0xcc00, v192
	v_mov_b32_e32 v0, 1.0
	v_mov_b32_e32 v36, 0
	s_waitcnt lgkmcnt(0)
	v_mul_f32_e32 v34, v37, v34
	v_mul_f32_e32 v34, v34, v38
	ds_write_b32 v188, v35 offset:52492
	ds_write_b32 v191, v34
	s_waitcnt lgkmcnt(0)
	s_barrier
; #define LBAR() do { asm volatile("s_waitcnt lgkmcnt(0)" ::: "memory"); __builtin_amdgcn_s_barrier(); asm volatile("" ::: "memory"); } while (0)
; DEVI void rnn_local_phase(const bf16_t* xr, const float* convw, const float* convb, const bf16_t* lruT, const float* ba, const float* bx, const float* lam,
;                           bf16_t* hloc, bf16_t* pcum, float* aggA, float* aggH, char* lds, int wv) {
;     ...
;         {
;             float h = 0.f, P = 1.f;
; #pragma unroll
;             for (int i = 0; i < 16; ++i) { const int o = (wave * 16 + i) * 65 + lane; const float a = aL[o], u = uL[o]; h = a * h + u; P *= a; uL[o] = h; aL[o] = P; }
;             segA[wave * 64 + lane] = P; segH[wave * 64 + lane] = h;
;         }
;         LBAR();
;         {
;             float Ain = 1.f, Hin = 0.f;
;             for (int s = 0; s < wave; ++s) { const float As = segA[s * 64 + lane], Hs = segH[s * 64 + lane]; Hin = As * Hin + Hs; Ain *= As; }
	v_add_u32_e32 v215, 0x14c00, v192
	ds_read_b32 v212, v192 offset:51712
	ds_read_b32 v213, v215
	ds_read_b32 v222, v192 offset:51972
	ds_read_b32 v223, v215 offset:260
	ds_read_b32 v224, v192 offset:52232
	ds_read_b32 v225, v215 offset:520
	ds_read_b32 v226, v192 offset:52492
	ds_read_b32 v227, v215 offset:780
	ds_read_b32 v228, v192 offset:52752
	ds_read_b32 v229, v215 offset:1040
	ds_read_b32 v230, v192 offset:53012
	ds_read_b32 v231, v215 offset:1300
	ds_read_b32 v232, v192 offset:53272
	ds_read_b32 v233, v215 offset:1560
	ds_read_b32 v234, v192 offset:53532
	ds_read_b32 v235, v215 offset:1820
	ds_read_b32 v236, v192 offset:53792
	ds_read_b32 v237, v215 offset:2080
	ds_read_b32 v238, v192 offset:54052
	ds_read_b32 v239, v215 offset:2340
	ds_read_b32 v240, v192 offset:54312
	ds_read_b32 v241, v215 offset:2600
	ds_read_b32 v242, v192 offset:54572
	ds_read_b32 v243, v215 offset:2860
	ds_read_b32 v244, v192 offset:54832
	ds_read_b32 v245, v215 offset:3120
	ds_read_b32 v246, v192 offset:55092
	ds_read_b32 v247, v215 offset:3380
	ds_read_b32 v248, v192 offset:55352
	ds_read_b32 v249, v215 offset:3640
	ds_read_b32 v250, v192 offset:55612
	ds_read_b32 v251, v215 offset:3900
	s_andn2_b64 vcc, exec, s[4:5]
	s_waitcnt lgkmcnt(15)
	v_fmac_f32_e32 v213, 0, v212
	v_fmac_f32_e32 v223, v213, v222
	v_mul_f32_e32 v222, v212, v222
	v_fmac_f32_e32 v225, v223, v224
	v_mul_f32_e32 v224, v222, v224
	v_fmac_f32_e32 v227, v225, v226
	v_mul_f32_e32 v226, v224, v226
	v_fmac_f32_e32 v229, v227, v228
	v_mul_f32_e32 v228, v226, v228
	v_fmac_f32_e32 v231, v229, v230
	v_mul_f32_e32 v230, v228, v230
	v_fmac_f32_e32 v233, v231, v232
	v_mul_f32_e32 v232, v230, v232
	v_fmac_f32_e32 v235, v233, v234
	v_mul_f32_e32 v234, v232, v234
	s_waitcnt lgkmcnt(14)
	v_fmac_f32_e32 v237, v235, v236
	v_mul_f32_e32 v236, v234, v236
	s_waitcnt lgkmcnt(12)
	v_fmac_f32_e32 v239, v237, v238
	v_mul_f32_e32 v238, v236, v238
	s_waitcnt lgkmcnt(10)
	v_fmac_f32_e32 v241, v239, v240
	v_mul_f32_e32 v240, v238, v240
	s_waitcnt lgkmcnt(8)
	v_fmac_f32_e32 v243, v241, v242
	v_mul_f32_e32 v242, v240, v242
	s_waitcnt lgkmcnt(6)
	v_fmac_f32_e32 v245, v243, v244
	v_mul_f32_e32 v244, v242, v244
	s_waitcnt lgkmcnt(4)
	v_fmac_f32_e32 v247, v245, v246
	v_mul_f32_e32 v246, v244, v246
	s_waitcnt lgkmcnt(2)
	v_fmac_f32_e32 v249, v247, v248
	v_mul_f32_e32 v248, v246, v248
	s_waitcnt lgkmcnt(0)
	v_fmac_f32_e32 v251, v249, v250
	v_mul_f32_e32 v250, v248, v250
	ds_write_b32 v166, v250
	ds_write_b32 v167, v251
	s_waitcnt lgkmcnt(0)
	s_barrier
	s_cbranch_vccnz .LBB0_190
	v_mov_b32_e32 v0, 1.0
	v_mov_b32_e32 v36, 0
	v_add_u32_e32 v215, 0xfffff800, v219
	ds_read_b32 v34, v215
	ds_read_b32 v35, v219
	ds_read_b32 v37, v215 offset:256
	ds_read_b32 v38, v219 offset:256
	ds_read_b32 v39, v215 offset:512
	ds_read_b32 v40, v219 offset:512
	ds_read_b32 v41, v215 offset:768
	ds_read_b32 v42, v219 offset:768
	ds_read_b32 v43, v215 offset:1024
	ds_read_b32 v44, v219 offset:1024
	ds_read_b32 v45, v215 offset:1280
	ds_read_b32 v198, v219 offset:1280
	ds_read_b32 v199, v215 offset:1536
	ds_read_b32 v214, v219 offset:1536
	s_waitcnt lgkmcnt(12)
	v_mul_f32_e32 v0, v0, v34
	v_fmac_f32_e32 v35, v36, v34
	v_mov_b32_e32 v36, v35
	s_cmp_le_u32 s46, 1
	s_cbranch_scc1 .Lmy_rnn_cdone
	s_waitcnt lgkmcnt(10)
	v_mul_f32_e32 v0, v0, v37
	v_fmac_f32_e32 v38, v36, v37
	v_mov_b32_e32 v36, v38
	s_cmp_le_u32 s46, 2
	s_cbranch_scc1 .Lmy_rnn_cdone
	s_waitcnt lgkmcnt(8)
	v_mul_f32_e32 v0, v0, v39
	v_fmac_f32_e32 v40, v36, v39
	v_mov_b32_e32 v36, v40
	s_cmp_le_u32 s46, 3
	s_cbranch_scc1 .Lmy_rnn_cdone
	s_waitcnt lgkmcnt(6)
	v_mul_f32_e32 v0, v0, v41
	v_fmac_f32_e32 v42, v36, v41
	v_mov_b32_e32 v36, v42
	s_cmp_le_u32 s46, 4
	s_cbranch_scc1 .Lmy_rnn_cdone
	s_waitcnt lgkmcnt(4)
	v_mul_f32_e32 v0, v0, v43
	v_fmac_f32_e32 v44, v36, v43
	v_mov_b32_e32 v36, v44
	s_cmp_le_u32 s46, 5
	s_cbranch_scc1 .Lmy_rnn_cdone
	s_waitcnt lgkmcnt(2)
	v_mul_f32_e32 v0, v0, v45
	v_fmac_f32_e32 v198, v36, v45
	v_mov_b32_e32 v36, v198
	s_cmp_le_u32 s46, 6
	s_cbranch_scc1 .Lmy_rnn_cdone
	s_waitcnt lgkmcnt(0)
	v_mul_f32_e32 v0, v0, v199
	v_fmac_f32_e32 v214, v36, v199
	v_mov_b32_e32 v36, v214

; DEVI unsigned cvtpk(float lo, float hi) { unsigned r; asm volatile("v_cvt_pk_bf16_f32 %0, %1, %2" : "=v"(r) : "v"(lo), "v"(hi)); return r; }
; DEVI void rnn_local_phase(const bf16_t* xr, const float* convw, const float* convb, const bf16_t* lruT, const float* ba, const float* bx, const float* lam,
;                           bf16_t* hloc, bf16_t* pcum, float* aggA, float* aggH, char* lds, int wv) {
;     ...
;             const size_t gbase = ((size_t)b * SEQ + t0 + wave * 16) * DM + ch0 + lane;
;             float hl = 0.f, pc = 0.f;
; #pragma unroll
;             for (int i = 0; i < 16; ++i) { const int o = (wave * 16 + i) * 65 + lane; hl = uL[o] + aL[o] * Hin; pc = aL[o] * Ain;
;                 hloc[gbase + (size_t)i * DM] = (bf16_t)(cvtpk(hl, hl) & 0xffffu); pcum[gbase + (size_t)i * DM] = (bf16_t)(cvtpk(pc, pc) & 0xffffu); }
;             if (wave == 7) { const size_t ao = ((size_t)b * 128 + chunk) * 1024 + ch0 + lane; aggA[ao] = pc; aggH[ao] = hl; }
.LBB0_190:
	s_ashr_i32 s10, s60, 7
	s_ashr_i32 s11, s10, 31
	s_add_u32 s80, s79, s25
	s_addc_u32 s81, 0, s61
	v_mov_b32_e32 v37, v213
	v_mov_b32_e32 v38, v212
	s_lshl_b64 s[82:83], s[10:11], 24
	s_lshl_b64 s[80:81], s[80:81], 10
	s_add_u32 s60, s80, s82
	s_addc_u32 s79, s81, s83
	v_mov_b32_e32 v35, s79
	v_or_b32_e32 v34, s60, v148
	v_fmac_f32_e32 v37, v36, v38
	v_lshlrev_b64 v[34:35], 1, v[34:35]
	v_mul_f32_e32 v40, v0, v38
	v_cvt_pk_bf16_f32 v37, v37, v37
	v_lshl_add_u64 v[38:39], s[14:15], 0, v[34:35]
	global_store_short v[38:39], v37, off
	v_cvt_pk_bf16_f32 v37, v40, v40
	v_mov_b32_e32 v40, v223
	v_mov_b32_e32 v41, v222
	v_lshl_add_u64 v[34:35], s[22:23], 0, v[34:35]
	global_store_short v[34:35], v37, off
	s_movk_i32 s60, 0x1000
	v_fmac_f32_e32 v40, v36, v41
	v_mul_f32_e32 v37, v0, v41
	v_cvt_pk_bf16_f32 v40, v40, v40
	global_store_short v[38:39], v40, off offset:2048
	v_cvt_pk_bf16_f32 v37, v37, v37
	v_mov_b32_e32 v40, v225
	v_mov_b32_e32 v41, v224
	global_store_short v[34:35], v37, off offset:2048
	v_fmac_f32_e32 v40, v36, v41
	v_cvt_pk_bf16_f32 v42, v40, v40
	v_add_co_u32_e32 v40, vcc, s60, v38
	v_mul_f32_e32 v37, v0, v41
	s_nop 0
	v_addc_co_u32_e32 v41, vcc, 0, v39, vcc
	global_store_short v[40:41], v42, off
	v_cvt_pk_bf16_f32 v37, v37, v37
	v_mov_b32_e32 v44, v227
	v_mov_b32_e32 v45, v226
	v_add_co_u32_e32 v42, vcc, s60, v34
	s_movk_i32 s60, 0x2000
	s_nop 0
	v_addc_co_u32_e32 v43, vcc, 0, v35, vcc
	global_store_short v[42:43], v37, off
	v_fmac_f32_e32 v44, v36, v45
	v_mul_f32_e32 v37, v0, v45
	v_cvt_pk_bf16_f32 v44, v44, v44
	global_store_short v[40:41], v44, off offset:2048
	v_cvt_pk_bf16_f32 v37, v37, v37
	v_mov_b32_e32 v40, v229
	v_mov_b32_e32 v41, v228
	global_store_short v[42:43], v37, off offset:2048
	v_fmac_f32_e32 v40, v36, v41
	v_cvt_pk_bf16_f32 v42, v40, v40
	v_add_co_u32_e32 v40, vcc, s60, v38
	v_mul_f32_e32 v37, v0, v41
	s_nop 0
	v_addc_co_u32_e32 v41, vcc, 0, v39, vcc
	global_store_short v[40:41], v42, off
	v_cvt_pk_bf16_f32 v37, v37, v37
	v_mov_b32_e32 v44, v231
	v_mov_b32_e32 v45, v230
	v_add_co_u32_e32 v42, vcc, s60, v34
	s_movk_i32 s60, 0x3000
	s_nop 0
	v_addc_co_u32_e32 v43, vcc, 0, v35, vcc
	global_store_short v[42:43], v37, off
	v_fmac_f32_e32 v44, v36, v45
	v_mul_f32_e32 v37, v0, v45
	v_cvt_pk_bf16_f32 v44, v44, v44
	global_store_short v[40:41], v44, off offset:2048
	v_cvt_pk_bf16_f32 v37, v37, v37
	v_mov_b32_e32 v40, v233
	v_mov_b32_e32 v41, v232
	global_store_short v[42:43], v37, off offset:2048
	v_fmac_f32_e32 v40, v36, v41
	v_cvt_pk_bf16_f32 v42, v40, v40
	v_add_co_u32_e32 v40, vcc, s60, v38
	v_mul_f32_e32 v37, v0, v41
	s_nop 0
	v_addc_co_u32_e32 v41, vcc, 0, v39, vcc
	global_store_short v[40:41], v42, off
	v_cvt_pk_bf16_f32 v37, v37, v37
	v_mov_b32_e32 v44, v235
	v_mov_b32_e32 v45, v234
	v_add_co_u32_e32 v42, vcc, s60, v34
	s_movk_i32 s60, 0x4000
	s_nop 0
	v_addc_co_u32_e32 v43, vcc, 0, v35, vcc
	global_store_short v[42:43], v37, off
	v_fmac_f32_e32 v44, v36, v45
	v_mul_f32_e32 v37, v0, v45
	v_cvt_pk_bf16_f32 v44, v44, v44
	global_store_short v[40:41], v44, off offset:2048
	v_cvt_pk_bf16_f32 v37, v37, v37
	v_mov_b32_e32 v40, v237
	v_mov_b32_e32 v41, v236
	global_store_short v[42:43], v37, off offset:2048
	v_fmac_f32_e32 v40, v36, v41
	v_cvt_pk_bf16_f32 v42, v40, v40
	v_add_co_u32_e32 v40, vcc, s60, v38
	v_mul_f32_e32 v37, v0, v41
	s_nop 0
	v_addc_co_u32_e32 v41, vcc, 0, v39, vcc
	global_store_short v[40:41], v42, off
	v_cvt_pk_bf16_f32 v37, v37, v37
	v_mov_b32_e32 v44, v239
	v_mov_b32_e32 v45, v238
	v_add_co_u32_e32 v42, vcc, s60, v34
	s_movk_i32 s60, 0x5000
	s_nop 0
	v_addc_co_u32_e32 v43, vcc, 0, v35, vcc
	global_store_short v[42:43], v37, off
	v_fmac_f32_e32 v44, v36, v45
	v_mul_f32_e32 v37, v0, v45
	v_cvt_pk_bf16_f32 v44, v44, v44
	global_store_short v[40:41], v44, off offset:2048
	v_cvt_pk_bf16_f32 v37, v37, v37
	v_mov_b32_e32 v40, v241
	v_mov_b32_e32 v41, v240
	global_store_short v[42:43], v37, off offset:2048
	v_fmac_f32_e32 v40, v36, v41
	v_cvt_pk_bf16_f32 v42, v40, v40
	v_add_co_u32_e32 v40, vcc, s60, v38
	v_mul_f32_e32 v37, v0, v41
	s_nop 0
	v_addc_co_u32_e32 v41, vcc, 0, v39, vcc
	global_store_short v[40:41], v42, off
	v_cvt_pk_bf16_f32 v37, v37, v37
	v_mov_b32_e32 v44, v243
	v_mov_b32_e32 v45, v242
	v_add_co_u32_e32 v42, vcc, s60, v34
	s_movk_i32 s60, 0x6000
	s_nop 0
	v_addc_co_u32_e32 v43, vcc, 0, v35, vcc
	global_store_short v[42:43], v37, off
	v_fmac_f32_e32 v44, v36, v45
	v_mul_f32_e32 v37, v0, v45
	v_cvt_pk_bf16_f32 v44, v44, v44
	global_store_short v[40:41], v44, off offset:2048
	v_cvt_pk_bf16_f32 v37, v37, v37
	v_mov_b32_e32 v40, v245
	v_mov_b32_e32 v41, v244
	global_store_short v[42:43], v37, off offset:2048
	v_fmac_f32_e32 v40, v36, v41
	v_cvt_pk_bf16_f32 v42, v40, v40
	v_add_co_u32_e32 v40, vcc, s60, v38
	v_mul_f32_e32 v37, v0, v41
	s_nop 0
	v_addc_co_u32_e32 v41, vcc, 0, v39, vcc
	global_store_short v[40:41], v42, off
	v_cvt_pk_bf16_f32 v37, v37, v37
	v_mov_b32_e32 v44, v247
	v_mov_b32_e32 v45, v246
	v_add_co_u32_e32 v42, vcc, s60, v34
	s_movk_i32 s60, 0x7000
	s_nop 0
	v_addc_co_u32_e32 v43, vcc, 0, v35, vcc
	global_store_short v[42:43], v37, off
	v_fmac_f32_e32 v44, v36, v45
	v_mul_f32_e32 v37, v0, v45
	v_cvt_pk_bf16_f32 v44, v44, v44
	global_store_short v[40:41], v44, off offset:2048
	v_cvt_pk_bf16_f32 v37, v37, v37
	v_mov_b32_e32 v40, v249
	v_mov_b32_e32 v41, v248
	v_add_co_u32_e32 v38, vcc, s60, v38
	global_store_short v[42:43], v37, off offset:2048
	s_nop 0
	v_addc_co_u32_e32 v39, vcc, 0, v39, vcc
	v_fmac_f32_e32 v40, v36, v41
	v_mul_f32_e32 v37, v0, v41
	v_cvt_pk_bf16_f32 v40, v40, v40
	global_store_short v[38:39], v40, off
	v_cvt_pk_bf16_f32 v37, v37, v37
	v_add_co_u32_e32 v40, vcc, 0x7000, v34
	v_mov_b32_e32 v34, v251
	v_mov_b32_e32 v42, v250
	v_addc_co_u32_e32 v41, vcc, 0, v35, vcc
	global_store_short v[40:41], v37, off
	s_and_b64 vcc, exec, s[6:7]
	v_fmac_f32_e32 v34, v36, v42
	v_mul_f32_e32 v0, v0, v42
	v_cvt_pk_bf16_f32 v35, v34, v34
	global_store_short v[38:39], v35, off offset:2048
	v_cvt_pk_bf16_f32 v35, v0, v0
	global_store_short v[40:41], v35, off offset:2048
	s_cbranch_vccz .LBB0_120
	s_lshl_b64 s[10:11], s[10:11], 17
	s_lshl_b32 s60, s78, 10
	s_or_b32 s10, s10, s60
	v_mov_b32_e32 v37, s11
	v_or_b32_e32 v36, s10, v148
	v_lshlrev_b64 v[36:37], 2, v[36:37]
	v_lshl_add_u64 v[38:39], s[18:19], 0, v[36:37]
	v_lshl_add_u64 v[36:37], s[20:21], 0, v[36:37]
	global_store_dword v[38:39], v0, off
	global_store_dword v[36:37], v34, off
	s_branch .LBB0_120
